# experiment: decode KV stream loads with sc1 nt (agent scope, streaming)
# speedup vs baseline: 1.0168x; 1.0135x over previous
.Ldc_nopf:
	s_ashr_i32 s7, s6, 31
	s_lshl_b64 s[6:7], s[6:7], 19
	s_add_u32 s12, s80, s6
	s_addc_u32 s13, s81, s7
	s_and_b32 s13, s13, 0xffff
	buffer_load_dwordx4 v[42:45], v247, s[12:15], 0 offen sc1 nt
	buffer_load_dwordx4 v[46:49], v247, s[12:15], s43 offen sc1 nt
	buffer_load_dwordx4 v[50:53], v247, s[12:15], s46 offen sc1 nt
	buffer_load_dwordx4 v[54:57], v247, s[12:15], s47 offen sc1 nt
	buffer_load_dwordx4 v[58:61], v247, s[12:15], s16 offen sc1 nt
	s_movk_i32 s16, 0x4800
	buffer_load_dwordx4 v[62:65], v247, s[12:15], s16 offen sc1 nt
	s_mov_b32 s16, 0x8800
	buffer_load_dwordx4 v[66:69], v247, s[12:15], s16 offen sc1 nt
	s_mov_b32 s16, 0xc800
	buffer_load_dwordx4 v[70:73], v247, s[12:15], s16 offen sc1 nt
	s_mov_b32 s16, 0x10800
	s_waitcnt vmcnt(7)
	v_cvt_pk_bf16_f32 v42, v42, v43
	v_cvt_pk_bf16_f32 v43, v44, v45
	ds_write_b64 v249, v[42:43]
	s_waitcnt vmcnt(6)
	v_cvt_pk_bf16_f32 v42, v46, v47
	v_cvt_pk_bf16_f32 v43, v48, v49
	ds_write_b64 v249, v[42:43] offset:576
	s_waitcnt vmcnt(5)
	v_cvt_pk_bf16_f32 v42, v50, v51
	v_cvt_pk_bf16_f32 v43, v52, v53
	ds_write_b64 v249, v[42:43] offset:1152
	s_waitcnt vmcnt(4)
	v_cvt_pk_bf16_f32 v42, v54, v55
	v_cvt_pk_bf16_f32 v43, v56, v57
	ds_write_b64 v249, v[42:43] offset:1728
	s_waitcnt vmcnt(3)
	v_cvt_pk_bf16_f32 v42, v58, v59
	v_cvt_pk_bf16_f32 v43, v60, v61
	ds_write_b64 v249, v[42:43] offset:2304
	s_waitcnt vmcnt(2)
	v_cvt_pk_bf16_f32 v42, v62, v63
	v_cvt_pk_bf16_f32 v43, v64, v65
	ds_write_b64 v249, v[42:43] offset:2880
	s_waitcnt vmcnt(1)
	v_cvt_pk_bf16_f32 v42, v66, v67
	v_cvt_pk_bf16_f32 v43, v68, v69
	ds_write_b64 v249, v[42:43] offset:3456
	s_waitcnt vmcnt(0)
	v_cvt_pk_bf16_f32 v74, v70, v71
	v_cvt_pk_bf16_f32 v75, v72, v73
	buffer_load_dwordx4 v[42:45], v247, s[12:15], s48 offen sc1 nt
	buffer_load_dwordx4 v[46:49], v247, s[12:15], s49 offen sc1 nt
	buffer_load_dwordx4 v[50:53], v247, s[12:15], s50 offen sc1 nt
	buffer_load_dwordx4 v[54:57], v247, s[12:15], s51 offen sc1 nt
	buffer_load_dwordx4 v[58:61], v247, s[12:15], s16 offen sc1 nt
	s_mov_b32 s16, 0x14800
	buffer_load_dwordx4 v[62:65], v247, s[12:15], s16 offen sc1 nt
	s_mov_b32 s16, 0x18800
	buffer_load_dwordx4 v[66:69], v247, s[12:15], s16 offen sc1 nt
	s_mov_b32 s16, 0x1c800
	buffer_load_dwordx4 v[70:73], v247, s[12:15], s16 offen sc1 nt
	ds_write_b64 v249, v[74:75] offset:4032
	s_waitcnt lgkmcnt(0)
	ds_read_b128 v[74:77], v250
	ds_read_b128 v[78:81], v250 offset:64
	s_waitcnt lgkmcnt(1)
	v_mfma_f32_16x16x32_bf16 v[74:77], v[74:77], v[2:5], 0
	ds_read_b128 v[82:85], v250 offset:2304
	s_add_u32 s16, s82, s6
	s_addc_u32 s6, s83, s7
	s_waitcnt lgkmcnt(1)
	v_mfma_f32_16x16x32_bf16 v[74:77], v[78:81], v[6:9], v[74:77]
	ds_read_b128 v[78:81], v250 offset:2368
	s_waitcnt lgkmcnt(1)
	v_mfma_f32_16x16x32_bf16 v[82:85], v[82:85], v[2:5], 0
	s_waitcnt lgkmcnt(0)
	v_mfma_f32_16x16x32_bf16 v[78:81], v[78:81], v[6:9], v[82:85]
	s_nop 7
	v_cndmask_b32_e64 v205, v81, v77, s[2:3]
	v_cndmask_b32_e64 v204, v80, v76, s[2:3]
	v_cndmask_b32_e64 v207, v79, v75, s[2:3]
	v_cndmask_b32_e64 v206, v78, v74, s[2:3]
	s_waitcnt vmcnt(7)
	v_cvt_pk_bf16_f32 v42, v42, v43
	v_cvt_pk_bf16_f32 v43, v44, v45
	ds_write_b64 v249, v[42:43] offset:4608
	s_waitcnt vmcnt(6)
	v_cvt_pk_bf16_f32 v42, v46, v47
	v_cvt_pk_bf16_f32 v43, v48, v49
	ds_write_b64 v249, v[42:43] offset:5184
	s_waitcnt vmcnt(5)
	v_cvt_pk_bf16_f32 v42, v50, v51
	v_cvt_pk_bf16_f32 v43, v52, v53
	ds_write_b64 v249, v[42:43] offset:5760
	s_waitcnt vmcnt(4)
	v_cvt_pk_bf16_f32 v42, v54, v55
	v_cvt_pk_bf16_f32 v43, v56, v57
	ds_write_b64 v249, v[42:43] offset:6336
	s_waitcnt vmcnt(3)
	v_cvt_pk_bf16_f32 v42, v58, v59
	v_cvt_pk_bf16_f32 v43, v60, v61
	ds_write_b64 v249, v[42:43] offset:6912
	s_waitcnt vmcnt(2)
	v_cvt_pk_bf16_f32 v42, v62, v63
	v_cvt_pk_bf16_f32 v43, v64, v65
	ds_write_b64 v249, v[42:43] offset:7488
	s_waitcnt vmcnt(1)
	v_cvt_pk_bf16_f32 v42, v66, v67
	v_cvt_pk_bf16_f32 v43, v68, v69
	s_mov_b32 s7, 0x20800
	ds_write_b64 v249, v[42:43] offset:8064
	s_waitcnt vmcnt(0)
	v_cvt_pk_bf16_f32 v74, v70, v71
	v_cvt_pk_bf16_f32 v75, v72, v73
	buffer_load_dwordx4 v[42:45], v247, s[12:15], s15 offen sc1 nt
	buffer_load_dwordx4 v[46:49], v247, s[12:15], s52 offen sc1 nt
	buffer_load_dwordx4 v[50:53], v247, s[12:15], s53 offen sc1 nt
	buffer_load_dwordx4 v[54:57], v247, s[12:15], s54 offen sc1 nt
	buffer_load_dwordx4 v[58:61], v247, s[12:15], s7 offen sc1 nt
	s_mov_b32 s7, 0x24800
	buffer_load_dwordx4 v[62:65], v247, s[12:15], s7 offen sc1 nt
	s_mov_b32 s7, 0x28800
	buffer_load_dwordx4 v[66:69], v247, s[12:15], s7 offen sc1 nt
	s_mov_b32 s7, 0x2c800
	buffer_load_dwordx4 v[70:73], v247, s[12:15], s7 offen sc1 nt
	ds_write_b64 v249, v[74:75] offset:8640
	s_waitcnt lgkmcnt(0)
	ds_read_b128 v[74:77], v250 offset:4608
	ds_read_b128 v[78:81], v250 offset:4672
	s_waitcnt lgkmcnt(1)
	v_mfma_f32_16x16x32_bf16 v[74:77], v[74:77], v[2:5], 0
	ds_read_b128 v[82:85], v250 offset:6912
	s_waitcnt lgkmcnt(1)
	v_mfma_f32_16x16x32_bf16 v[74:77], v[78:81], v[6:9], v[74:77]
	ds_read_b128 v[78:81], v250 offset:6976
	s_waitcnt lgkmcnt(1)
	v_mfma_f32_16x16x32_bf16 v[82:85], v[82:85], v[2:5], 0
	s_waitcnt lgkmcnt(0)
	v_mfma_f32_16x16x32_bf16 v[78:81], v[78:81], v[6:9], v[82:85]
	s_nop 7
	v_cndmask_b32_e64 v209, v81, v77, s[2:3]
	v_cndmask_b32_e64 v208, v80, v76, s[2:3]
	v_cndmask_b32_e64 v211, v79, v75, s[2:3]
	v_cndmask_b32_e64 v210, v78, v74, s[2:3]
	s_waitcnt vmcnt(7)
	v_cvt_pk_bf16_f32 v42, v42, v43
	v_cvt_pk_bf16_f32 v43, v44, v45
	ds_write_b64 v249, v[42:43]
	s_waitcnt vmcnt(6)
	v_cvt_pk_bf16_f32 v42, v46, v47
	v_cvt_pk_bf16_f32 v43, v48, v49
	ds_write_b64 v249, v[42:43] offset:576
	s_waitcnt vmcnt(5)
	v_cvt_pk_bf16_f32 v42, v50, v51
	v_cvt_pk_bf16_f32 v43, v52, v53
	ds_write_b64 v249, v[42:43] offset:1152
	s_waitcnt vmcnt(4)
	v_cvt_pk_bf16_f32 v42, v54, v55
	v_cvt_pk_bf16_f32 v43, v56, v57
	ds_write_b64 v249, v[42:43] offset:1728
	s_waitcnt vmcnt(3)
	v_cvt_pk_bf16_f32 v42, v58, v59
	v_cvt_pk_bf16_f32 v43, v60, v61
	ds_write_b64 v249, v[42:43] offset:2304
	s_waitcnt vmcnt(2)
	v_cvt_pk_bf16_f32 v42, v62, v63
	v_cvt_pk_bf16_f32 v43, v64, v65
	ds_write_b64 v249, v[42:43] offset:2880
	s_waitcnt vmcnt(1)
	v_cvt_pk_bf16_f32 v42, v66, v67
	v_cvt_pk_bf16_f32 v43, v68, v69
	s_mov_b32 s7, 0x30800
	ds_write_b64 v249, v[42:43] offset:3456
	s_waitcnt vmcnt(0)
	v_cvt_pk_bf16_f32 v74, v70, v71
	v_cvt_pk_bf16_f32 v75, v72, v73
	buffer_load_dwordx4 v[42:45], v247, s[12:15], s55 offen sc1 nt
	buffer_load_dwordx4 v[46:49], v247, s[12:15], s56 offen sc1 nt
	buffer_load_dwordx4 v[50:53], v247, s[12:15], s57 offen sc1 nt
	buffer_load_dwordx4 v[54:57], v247, s[12:15], s62 offen sc1 nt
	buffer_load_dwordx4 v[58:61], v247, s[12:15], s7 offen sc1 nt
	s_mov_b32 s7, 0x34800
	buffer_load_dwordx4 v[62:65], v247, s[12:15], s7 offen sc1 nt
	s_mov_b32 s7, 0x38800
	buffer_load_dwordx4 v[66:69], v247, s[12:15], s7 offen sc1 nt
	s_mov_b32 s7, 0x3c800
	buffer_load_dwordx4 v[70:73], v247, s[12:15], s7 offen sc1 nt
	ds_write_b64 v249, v[74:75] offset:4032
	s_waitcnt lgkmcnt(0)
	ds_read_b128 v[74:77], v250
	ds_read_b128 v[78:81], v250 offset:64
	s_waitcnt lgkmcnt(1)
	v_mfma_f32_16x16x32_bf16 v[74:77], v[74:77], v[2:5], 0
	ds_read_b128 v[82:85], v250 offset:2304
	s_waitcnt lgkmcnt(1)
	v_mfma_f32_16x16x32_bf16 v[74:77], v[78:81], v[6:9], v[74:77]
	ds_read_b128 v[78:81], v250 offset:2368
	s_waitcnt lgkmcnt(1)
	v_mfma_f32_16x16x32_bf16 v[82:85], v[82:85], v[2:5], 0
	s_waitcnt lgkmcnt(0)
	v_mfma_f32_16x16x32_bf16 v[78:81], v[78:81], v[6:9], v[82:85]
	s_nop 7
	v_cndmask_b32_e64 v213, v81, v77, s[2:3]
	v_cndmask_b32_e64 v212, v80, v76, s[2:3]
	v_cndmask_b32_e64 v215, v79, v75, s[2:3]
	v_cndmask_b32_e64 v214, v78, v74, s[2:3]
	s_waitcnt vmcnt(7)
	v_cvt_pk_bf16_f32 v42, v42, v43
	v_cvt_pk_bf16_f32 v43, v44, v45
	ds_write_b64 v249, v[42:43] offset:4608
	s_waitcnt vmcnt(6)
	v_cvt_pk_bf16_f32 v42, v46, v47
	v_cvt_pk_bf16_f32 v43, v48, v49
	ds_write_b64 v249, v[42:43] offset:5184
	s_waitcnt vmcnt(5)
	v_cvt_pk_bf16_f32 v42, v50, v51
	v_cvt_pk_bf16_f32 v43, v52, v53
	ds_write_b64 v249, v[42:43] offset:5760
	s_waitcnt vmcnt(4)
	v_cvt_pk_bf16_f32 v42, v54, v55
	v_cvt_pk_bf16_f32 v43, v56, v57
	ds_write_b64 v249, v[42:43] offset:6336
	s_waitcnt vmcnt(3)
	v_cvt_pk_bf16_f32 v42, v58, v59
	v_cvt_pk_bf16_f32 v43, v60, v61
	ds_write_b64 v249, v[42:43] offset:6912
	s_waitcnt vmcnt(2)
	v_cvt_pk_bf16_f32 v42, v62, v63
	v_cvt_pk_bf16_f32 v43, v64, v65
	ds_write_b64 v249, v[42:43] offset:7488
	s_waitcnt vmcnt(1)
	v_cvt_pk_bf16_f32 v42, v66, v67
	v_cvt_pk_bf16_f32 v43, v68, v69
	s_mov_b32 s7, 0x40800
	ds_write_b64 v249, v[42:43] offset:8064
	s_waitcnt vmcnt(0)
	v_cvt_pk_bf16_f32 v74, v70, v71
	v_cvt_pk_bf16_f32 v75, v72, v73
	buffer_load_dwordx4 v[42:45], v247, s[12:15], s63 offen sc1 nt
	buffer_load_dwordx4 v[46:49], v247, s[12:15], s64 offen sc1 nt
	buffer_load_dwordx4 v[50:53], v247, s[12:15], s65 offen sc1 nt
	buffer_load_dwordx4 v[54:57], v247, s[12:15], s66 offen sc1 nt
	buffer_load_dwordx4 v[58:61], v247, s[12:15], s7 offen sc1 nt
	s_mov_b32 s7, 0x44800
	buffer_load_dwordx4 v[62:65], v247, s[12:15], s7 offen sc1 nt
	s_mov_b32 s7, 0x48800
	buffer_load_dwordx4 v[66:69], v247, s[12:15], s7 offen sc1 nt
	s_mov_b32 s7, 0x4c800
	buffer_load_dwordx4 v[70:73], v247, s[12:15], s7 offen sc1 nt
	ds_write_b64 v249, v[74:75] offset:8640
	s_waitcnt lgkmcnt(0)
	ds_read_b128 v[74:77], v250 offset:4608
	ds_read_b128 v[78:81], v250 offset:4672
	s_waitcnt lgkmcnt(1)
	v_mfma_f32_16x16x32_bf16 v[74:77], v[74:77], v[2:5], 0
	ds_read_b128 v[82:85], v250 offset:6912
	s_waitcnt lgkmcnt(1)
	v_mfma_f32_16x16x32_bf16 v[74:77], v[78:81], v[6:9], v[74:77]
	ds_read_b128 v[78:81], v250 offset:6976
	s_waitcnt lgkmcnt(1)
	v_mfma_f32_16x16x32_bf16 v[82:85], v[82:85], v[2:5], 0
	s_waitcnt lgkmcnt(0)
	v_mfma_f32_16x16x32_bf16 v[78:81], v[78:81], v[6:9], v[82:85]
	s_nop 7
	v_cndmask_b32_e64 v217, v81, v77, s[2:3]
	v_cndmask_b32_e64 v216, v80, v76, s[2:3]
	v_cndmask_b32_e64 v219, v79, v75, s[2:3]
	v_cndmask_b32_e64 v218, v78, v74, s[2:3]
	s_waitcnt vmcnt(7)
	v_cvt_pk_bf16_f32 v42, v42, v43
	v_cvt_pk_bf16_f32 v43, v44, v45
	ds_write_b64 v249, v[42:43]
	s_waitcnt vmcnt(6)
	v_cvt_pk_bf16_f32 v42, v46, v47
	v_cvt_pk_bf16_f32 v43, v48, v49
	ds_write_b64 v249, v[42:43] offset:576
	s_waitcnt vmcnt(5)
	v_cvt_pk_bf16_f32 v42, v50, v51
	v_cvt_pk_bf16_f32 v43, v52, v53
	ds_write_b64 v249, v[42:43] offset:1152
	s_waitcnt vmcnt(4)
	v_cvt_pk_bf16_f32 v42, v54, v55
	v_cvt_pk_bf16_f32 v43, v56, v57
	ds_write_b64 v249, v[42:43] offset:1728
	s_waitcnt vmcnt(3)
	v_cvt_pk_bf16_f32 v42, v58, v59
	v_cvt_pk_bf16_f32 v43, v60, v61
	ds_write_b64 v249, v[42:43] offset:2304
	s_waitcnt vmcnt(2)
	v_cvt_pk_bf16_f32 v42, v62, v63
	v_cvt_pk_bf16_f32 v43, v64, v65
	ds_write_b64 v249, v[42:43] offset:2880
	s_waitcnt vmcnt(1)
	v_cvt_pk_bf16_f32 v42, v66, v67
	v_cvt_pk_bf16_f32 v43, v68, v69
	s_mov_b32 s7, 0x50800
	ds_write_b64 v249, v[42:43] offset:3456
	s_waitcnt vmcnt(0)
	v_cvt_pk_bf16_f32 v74, v70, v71
	v_cvt_pk_bf16_f32 v75, v72, v73
	buffer_load_dwordx4 v[42:45], v247, s[12:15], s67 offen sc1 nt
	buffer_load_dwordx4 v[46:49], v247, s[12:15], s68 offen sc1 nt
	buffer_load_dwordx4 v[50:53], v247, s[12:15], s69 offen sc1 nt
	buffer_load_dwordx4 v[54:57], v247, s[12:15], s84 offen sc1 nt
	buffer_load_dwordx4 v[58:61], v247, s[12:15], s7 offen sc1 nt
	s_mov_b32 s7, 0x54800
	buffer_load_dwordx4 v[62:65], v247, s[12:15], s7 offen sc1 nt
	s_mov_b32 s7, 0x58800
	buffer_load_dwordx4 v[66:69], v247, s[12:15], s7 offen sc1 nt
	s_mov_b32 s7, 0x5c800
	buffer_load_dwordx4 v[70:73], v247, s[12:15], s7 offen sc1 nt
	ds_write_b64 v249, v[74:75] offset:4032
	s_waitcnt lgkmcnt(0)
	ds_read_b128 v[74:77], v250
	ds_read_b128 v[78:81], v250 offset:64
	s_waitcnt lgkmcnt(1)
	v_mfma_f32_16x16x32_bf16 v[74:77], v[74:77], v[2:5], 0
	ds_read_b128 v[82:85], v250 offset:2304
	s_waitcnt lgkmcnt(1)
	v_mfma_f32_16x16x32_bf16 v[74:77], v[78:81], v[6:9], v[74:77]
	ds_read_b128 v[78:81], v250 offset:2368
	s_waitcnt lgkmcnt(1)
	v_mfma_f32_16x16x32_bf16 v[82:85], v[82:85], v[2:5], 0
	s_waitcnt lgkmcnt(0)
	v_mfma_f32_16x16x32_bf16 v[78:81], v[78:81], v[6:9], v[82:85]
	s_nop 7
	v_cndmask_b32_e64 v221, v81, v77, s[2:3]
	v_cndmask_b32_e64 v220, v80, v76, s[2:3]
	v_cndmask_b32_e64 v223, v79, v75, s[2:3]
	v_cndmask_b32_e64 v222, v78, v74, s[2:3]
	s_waitcnt vmcnt(7)
	v_cvt_pk_bf16_f32 v42, v42, v43
	v_cvt_pk_bf16_f32 v43, v44, v45
	ds_write_b64 v249, v[42:43] offset:4608
	s_waitcnt vmcnt(6)
	v_cvt_pk_bf16_f32 v42, v46, v47
	v_cvt_pk_bf16_f32 v43, v48, v49
	ds_write_b64 v249, v[42:43] offset:5184
	s_waitcnt vmcnt(5)
	v_cvt_pk_bf16_f32 v42, v50, v51
	v_cvt_pk_bf16_f32 v43, v52, v53
	ds_write_b64 v249, v[42:43] offset:5760
	s_waitcnt vmcnt(4)
	v_cvt_pk_bf16_f32 v42, v54, v55
	v_cvt_pk_bf16_f32 v43, v56, v57
	ds_write_b64 v249, v[42:43] offset:6336
	s_waitcnt vmcnt(3)
	v_cvt_pk_bf16_f32 v42, v58, v59
	v_cvt_pk_bf16_f32 v43, v60, v61
	ds_write_b64 v249, v[42:43] offset:6912
	s_waitcnt vmcnt(2)
	v_cvt_pk_bf16_f32 v42, v62, v63
	v_cvt_pk_bf16_f32 v43, v64, v65
	ds_write_b64 v249, v[42:43] offset:7488
	s_waitcnt vmcnt(1)
	v_cvt_pk_bf16_f32 v42, v66, v67
	v_cvt_pk_bf16_f32 v43, v68, v69
	s_mov_b32 s7, 0x60800
	ds_write_b64 v249, v[42:43] offset:8064
	s_waitcnt vmcnt(0)
	v_cvt_pk_bf16_f32 v74, v70, v71
	v_cvt_pk_bf16_f32 v75, v72, v73
	buffer_load_dwordx4 v[42:45], v247, s[12:15], s85 offen sc1 nt
	buffer_load_dwordx4 v[46:49], v247, s[12:15], s86 offen sc1 nt
	buffer_load_dwordx4 v[50:53], v247, s[12:15], s87 offen sc1 nt
	buffer_load_dwordx4 v[54:57], v247, s[12:15], s92 offen sc1 nt
	buffer_load_dwordx4 v[58:61], v247, s[12:15], s7 offen sc1 nt
	s_mov_b32 s7, 0x64800
	buffer_load_dwordx4 v[62:65], v247, s[12:15], s7 offen sc1 nt
	s_mov_b32 s7, 0x68800
	buffer_load_dwordx4 v[66:69], v247, s[12:15], s7 offen sc1 nt
	s_mov_b32 s7, 0x6c800
	buffer_load_dwordx4 v[70:73], v247, s[12:15], s7 offen sc1 nt
	ds_write_b64 v249, v[74:75] offset:8640
	s_waitcnt lgkmcnt(0)
	ds_read_b128 v[74:77], v250 offset:4608
	ds_read_b128 v[78:81], v250 offset:4672
	s_waitcnt lgkmcnt(1)
	v_mfma_f32_16x16x32_bf16 v[74:77], v[74:77], v[2:5], 0
	ds_read_b128 v[82:85], v250 offset:6912
	s_waitcnt lgkmcnt(1)
	v_mfma_f32_16x16x32_bf16 v[74:77], v[78:81], v[6:9], v[74:77]
	ds_read_b128 v[78:81], v250 offset:6976
	s_waitcnt lgkmcnt(1)
	v_mfma_f32_16x16x32_bf16 v[82:85], v[82:85], v[2:5], 0
	s_waitcnt lgkmcnt(0)
	v_mfma_f32_16x16x32_bf16 v[78:81], v[78:81], v[6:9], v[82:85]
	s_nop 7
	v_cndmask_b32_e64 v225, v81, v77, s[2:3]
	v_cndmask_b32_e64 v224, v80, v76, s[2:3]
	v_cndmask_b32_e64 v227, v79, v75, s[2:3]
	v_cndmask_b32_e64 v226, v78, v74, s[2:3]
	s_waitcnt vmcnt(7)
	v_cvt_pk_bf16_f32 v42, v42, v43
	v_cvt_pk_bf16_f32 v43, v44, v45
	ds_write_b64 v249, v[42:43]
	s_waitcnt vmcnt(6)
	v_cvt_pk_bf16_f32 v42, v46, v47
	v_cvt_pk_bf16_f32 v43, v48, v49
	ds_write_b64 v249, v[42:43] offset:576
	s_waitcnt vmcnt(5)
	v_cvt_pk_bf16_f32 v42, v50, v51
	v_cvt_pk_bf16_f32 v43, v52, v53
	ds_write_b64 v249, v[42:43] offset:1152
	s_waitcnt vmcnt(4)
	v_cvt_pk_bf16_f32 v42, v54, v55
	v_cvt_pk_bf16_f32 v43, v56, v57
	ds_write_b64 v249, v[42:43] offset:1728
	s_waitcnt vmcnt(3)
	v_cvt_pk_bf16_f32 v42, v58, v59
	v_cvt_pk_bf16_f32 v43, v60, v61
	ds_write_b64 v249, v[42:43] offset:2304
	s_waitcnt vmcnt(2)
	v_cvt_pk_bf16_f32 v42, v62, v63
	v_cvt_pk_bf16_f32 v43, v64, v65
	ds_write_b64 v249, v[42:43] offset:2880
	s_waitcnt vmcnt(1)
	v_cvt_pk_bf16_f32 v42, v66, v67
	v_cvt_pk_bf16_f32 v43, v68, v69
	s_mov_b32 s7, 0x70800
	ds_write_b64 v249, v[42:43] offset:3456
	s_waitcnt vmcnt(0)
	v_cvt_pk_bf16_f32 v74, v70, v71
	v_cvt_pk_bf16_f32 v75, v72, v73
	buffer_load_dwordx4 v[42:45], v247, s[12:15], s94 offen sc1 nt
	buffer_load_dwordx4 v[46:49], v247, s[12:15], s95 offen sc1 nt
	buffer_load_dwordx4 v[50:53], v247, s[12:15], s96 offen sc1 nt
	buffer_load_dwordx4 v[54:57], v247, s[12:15], s97 offen sc1 nt
	buffer_load_dwordx4 v[58:61], v247, s[12:15], s7 offen sc1 nt
	s_mov_b32 s7, 0x74800
	buffer_load_dwordx4 v[62:65], v247, s[12:15], s7 offen sc1 nt
	s_mov_b32 s7, 0x78800
	buffer_load_dwordx4 v[66:69], v247, s[12:15], s7 offen sc1 nt
	s_mov_b32 s7, 0x7c800
	buffer_load_dwordx4 v[70:73], v247, s[12:15], s7 offen sc1 nt
	ds_write_b64 v249, v[74:75] offset:4032
	s_waitcnt lgkmcnt(0)
	ds_read_b128 v[74:77], v250
	ds_read_b128 v[78:81], v250 offset:64
	s_waitcnt lgkmcnt(1)
	v_mfma_f32_16x16x32_bf16 v[74:77], v[74:77], v[2:5], 0
	ds_read_b128 v[82:85], v250 offset:2304
	s_waitcnt lgkmcnt(1)
	v_mfma_f32_16x16x32_bf16 v[74:77], v[78:81], v[6:9], v[74:77]
	ds_read_b128 v[78:81], v250 offset:2368
	s_waitcnt lgkmcnt(1)
	v_mfma_f32_16x16x32_bf16 v[82:85], v[82:85], v[2:5], 0
	s_waitcnt lgkmcnt(0)
	v_mfma_f32_16x16x32_bf16 v[78:81], v[78:81], v[6:9], v[82:85]
	s_nop 7
	v_cndmask_b32_e64 v233, v81, v77, s[2:3]
	v_cndmask_b32_e64 v232, v80, v76, s[2:3]
	v_cndmask_b32_e64 v235, v79, v75, s[2:3]
	v_cndmask_b32_e64 v234, v78, v74, s[2:3]
	s_waitcnt vmcnt(7)
	v_cvt_pk_bf16_f32 v42, v42, v43
	v_cvt_pk_bf16_f32 v43, v44, v45
	ds_write_b64 v249, v[42:43] offset:4608
	s_waitcnt vmcnt(6)
	v_cvt_pk_bf16_f32 v42, v46, v47
	v_cvt_pk_bf16_f32 v43, v48, v49
	ds_write_b64 v249, v[42:43] offset:5184
	s_waitcnt vmcnt(5)
	v_cvt_pk_bf16_f32 v42, v50, v51
	v_cvt_pk_bf16_f32 v43, v52, v53
	ds_write_b64 v249, v[42:43] offset:5760
	s_waitcnt vmcnt(4)
	v_cvt_pk_bf16_f32 v42, v54, v55
	v_cvt_pk_bf16_f32 v43, v56, v57
	ds_write_b64 v249, v[42:43] offset:6336
	s_waitcnt vmcnt(3)
	v_cvt_pk_bf16_f32 v42, v58, v59
	v_cvt_pk_bf16_f32 v43, v60, v61
	ds_write_b64 v249, v[42:43] offset:6912
	s_waitcnt vmcnt(2)
	v_cvt_pk_bf16_f32 v42, v62, v63
	v_cvt_pk_bf16_f32 v43, v64, v65
	ds_write_b64 v249, v[42:43] offset:7488
	s_waitcnt vmcnt(1)
	v_cvt_pk_bf16_f32 v42, v66, v67
	v_cvt_pk_bf16_f32 v43, v68, v69
	ds_write_b64 v249, v[42:43] offset:8064
	s_waitcnt vmcnt(0)
	v_cvt_pk_bf16_f32 v42, v70, v71
	v_cvt_pk_bf16_f32 v43, v72, v73
	ds_write_b64 v249, v[42:43] offset:8640
	s_waitcnt lgkmcnt(0)
	ds_read_b128 v[42:45], v250 offset:4608
	ds_read_b128 v[46:49], v250 offset:4672
	s_waitcnt lgkmcnt(1)
	v_mfma_f32_16x16x32_bf16 v[42:45], v[42:45], v[2:5], 0
	ds_read_b128 v[50:53], v250 offset:6912
	s_waitcnt lgkmcnt(1)
	v_mfma_f32_16x16x32_bf16 v[42:45], v[46:49], v[6:9], v[42:45]
	ds_read_b128 v[46:49], v250 offset:6976
	s_waitcnt lgkmcnt(1)
	v_mfma_f32_16x16x32_bf16 v[50:53], v[50:53], v[2:5], 0
	s_waitcnt lgkmcnt(0)
	v_mfma_f32_16x16x32_bf16 v[46:49], v[46:49], v[6:9], v[50:53]
	s_nop 7
	v_cndmask_b32_e64 v231, v49, v45, s[2:3]
	v_cndmask_b32_e64 v230, v48, v44, s[2:3]
	v_cndmask_b32_e64 v229, v47, v43, s[2:3]
	v_cndmask_b32_e64 v228, v46, v42, s[2:3]
	s_and_b32 s17, s6, 0xffff
	s_mov_b32 s18, s14
	s_mov_b32 s19, s15
	s_movk_i32 s6, 0x2000
	buffer_load_dwordx4 v[98:101], v248, s[16:19], 0 offen sc1 nt
	buffer_load_dwordx4 v[94:97], v248, s[16:19], s6 offen sc1 nt
	buffer_load_dwordx4 v[90:93], v248, s[16:19], s43 offen sc1 nt
	buffer_load_dwordx4 v[86:89], v248, s[16:19], s46 offen sc1 nt
	s_mov_b32 s6, 0xa000
	buffer_load_dwordx4 v[82:85], v248, s[16:19], s6 offen sc1 nt
	s_mov_b32 s6, 0xe000
	buffer_load_dwordx4 v[74:77], v248, s[16:19], s6 offen sc1 nt
	buffer_load_dwordx4 v[78:81], v248, s[16:19], s47 offen sc1 nt
	buffer_load_dwordx4 v[70:73], v248, s[16:19], s48 offen sc1 nt
	s_mov_b32 s6, 0x12000
	buffer_load_dwordx4 v[66:69], v248, s[16:19], s6 offen sc1 nt
	s_mov_b32 s6, 0x16000
	buffer_load_dwordx4 v[58:61], v248, s[16:19], s6 offen sc1 nt
	buffer_load_dwordx4 v[62:65], v248, s[16:19], s49 offen sc1 nt
	buffer_load_dwordx4 v[54:57], v248, s[16:19], s50 offen sc1 nt
	s_movk_i32 s6, 0x6000
	buffer_load_dwordx4 v[102:105], v248, s[16:19], s6 offen sc1 nt
	buffer_load_dwordx4 v[46:49], v248, s[16:19], s51 offen sc1 nt
	s_mov_b32 s6, 0x1a000
	buffer_load_dwordx4 v[50:53], v248, s[16:19], s6 offen sc1 nt
	s_mov_b32 s6, 0x1e000
	buffer_load_dwordx4 v[42:45], v248, s[16:19], s6 offen sc1 nt
	s_cmp_eq_u32 s39, s5
	s_mov_b64 s[6:7], -1
	s_cbranch_scc1 .LBB0_723
	v_pk_add_f32 v[124:125], v[144:145], v[204:205]
	v_pk_add_f32 v[122:123], v[142:143], v[206:207]
	v_pk_add_f32 v[120:121], v[144:145], v[208:209]
	v_pk_add_f32 v[118:119], v[142:143], v[210:211]
	v_pk_add_f32 v[116:117], v[144:145], v[212:213]
	v_pk_add_f32 v[114:115], v[142:143], v[214:215]
	v_pk_add_f32 v[112:113], v[144:145], v[216:217]
	v_pk_add_f32 v[110:111], v[142:143], v[218:219]
	v_pk_add_f32 v[108:109], v[144:145], v[220:221]
	v_pk_add_f32 v[106:107], v[142:143], v[222:223]
	v_pk_add_f32 v[128:129], v[144:145], v[224:225]
	v_pk_add_f32 v[126:127], v[142:143], v[226:227]
	v_pk_add_f32 v[132:133], v[144:145], v[232:233]
	v_pk_add_f32 v[130:131], v[142:143], v[234:235]
	v_pk_add_f32 v[136:137], v[144:145], v[230:231]
	v_pk_add_f32 v[134:135], v[142:143], v[228:229]
	s_mov_b64 s[6:7], 0

.LBB0_725:
	v_max_f32_e32 v204, v125, v125
	v_max_f32_e32 v205, v124, v124
	v_max_f32_e32 v204, v205, v204
	v_max_f32_e32 v205, v121, v121
	v_max_f32_e32 v206, v120, v120
	v_max_f32_e32 v205, v206, v205
	v_max3_f32 v204, v122, v123, v204
	v_max3_f32 v205, v118, v119, v205
	s_mov_b32 s6, 0xf149f2ca
	v_max3_f32 v204, v204, s6, v205
	v_max_f32_e32 v205, v117, v117
	v_max_f32_e32 v206, v116, v116
	v_max_f32_e32 v205, v206, v205
	v_max_f32_e32 v206, v113, v113
	v_max_f32_e32 v207, v112, v112
	v_max_f32_e32 v206, v207, v206
	v_max3_f32 v205, v114, v115, v205
	v_max3_f32 v206, v110, v111, v206
	v_max3_f32 v204, v204, v205, v206
	v_max_f32_e32 v205, v109, v109
	v_max_f32_e32 v206, v108, v108
	v_max_f32_e32 v205, v206, v205
	v_max_f32_e32 v206, v129, v129
	v_max_f32_e32 v207, v128, v128
	v_max_f32_e32 v206, v207, v206
	v_max3_f32 v205, v106, v107, v205
	v_max3_f32 v206, v126, v127, v206
	v_max3_f32 v204, v204, v205, v206
	v_max_f32_e32 v205, v133, v133
	v_max_f32_e32 v206, v132, v132
	v_max_f32_e32 v205, v206, v205
	v_max_f32_e32 v206, v137, v137
	v_max_f32_e32 v207, v136, v136
	v_max_f32_e32 v206, v207, v206
	v_max3_f32 v205, v130, v131, v205
	v_max3_f32 v206, v134, v135, v206
	v_max3_f32 v204, v204, v205, v206
	v_and_b32_e32 v206, 64, v243
	v_xor_b32_e32 v205, 16, v243
	v_add_u32_e32 v207, 64, v206
	v_cmp_lt_i32_e32 vcc, v205, v207
	s_mov_b32 s18, s14
	s_mov_b32 s19, s15
	v_cndmask_b32_e32 v205, v243, v205, vcc
	v_lshlrev_b32_e32 v206, 2, v205
	ds_bpermute_b32 v205, v206, v204
	s_mov_b32 s6, 0x22000
	s_waitcnt lgkmcnt(0)
	v_max_f32_e32 v205, v205, v205
	v_max_f32_e32 v204, v204, v205
	v_xor_b32_e32 v205, 32, v243
	v_cmp_lt_i32_e32 vcc, v205, v207
	s_nop 1
	v_cndmask_b32_e32 v205, v243, v205, vcc
	v_lshlrev_b32_e32 v207, 2, v205
	ds_bpermute_b32 v205, v207, v204
	s_waitcnt lgkmcnt(0)
	v_max3_f32 v205, v236, v204, v205
	v_sub_f32_e32 v122, v122, v205
	v_exp_f32_e32 v221, v122
	v_sub_f32_e32 v123, v123, v205
	v_exp_f32_e32 v222, v123
	v_sub_f32_e32 v123, v124, v205
	v_exp_f32_e32 v223, v123
	v_sub_f32_e32 v123, v125, v205
	v_exp_f32_e32 v224, v123
	v_sub_f32_e32 v118, v118, v205
	v_add_f32_e32 v122, 0, v221
	v_exp_f32_e32 v225, v118
	v_sub_f32_e32 v119, v119, v205
	v_add_f32_e32 v122, v222, v122
	v_exp_f32_e32 v226, v119
	v_sub_f32_e32 v119, v120, v205
	v_add_f32_e32 v122, v223, v122
	v_exp_f32_e32 v227, v119
	v_sub_f32_e32 v119, v121, v205
	v_add_f32_e32 v122, v224, v122
	v_exp_f32_e32 v228, v119
	v_sub_f32_e32 v114, v114, v205
	v_add_f32_e32 v118, v225, v122
	v_exp_f32_e32 v213, v114
	v_sub_f32_e32 v115, v115, v205
	v_add_f32_e32 v118, v226, v118
	v_exp_f32_e32 v214, v115
	v_sub_f32_e32 v115, v116, v205
	v_add_f32_e32 v118, v227, v118
	v_exp_f32_e32 v215, v115
	v_sub_f32_e32 v115, v117, v205
	v_add_f32_e32 v118, v228, v118
	v_exp_f32_e32 v216, v115
	v_sub_f32_e32 v110, v110, v205
	v_add_f32_e32 v114, v213, v118
	v_exp_f32_e32 v217, v110
	v_sub_f32_e32 v111, v111, v205
	v_add_f32_e32 v114, v214, v114
	v_exp_f32_e32 v218, v111
	v_sub_f32_e32 v111, v112, v205
	v_add_f32_e32 v114, v215, v114
	v_exp_f32_e32 v219, v111
	v_sub_f32_e32 v111, v113, v205
	v_add_f32_e32 v114, v216, v114
	v_exp_f32_e32 v220, v111
	v_sub_f32_e32 v106, v106, v205
	v_add_f32_e32 v110, v217, v114
	v_exp_f32_e32 v208, v106
	v_sub_f32_e32 v107, v107, v205
	v_add_f32_e32 v110, v218, v110
	v_exp_f32_e32 v209, v107
	v_sub_f32_e32 v107, v108, v205
	v_add_f32_e32 v110, v219, v110
	v_exp_f32_e32 v210, v107
	v_sub_f32_e32 v107, v109, v205
	v_add_f32_e32 v110, v220, v110
	v_exp_f32_e32 v211, v107
	v_sub_f32_e32 v107, v126, v205
	v_add_f32_e32 v106, v208, v110
	v_exp_f32_e32 v212, v107
	v_sub_f32_e32 v107, v127, v205
	v_add_f32_e32 v106, v209, v106
	v_exp_f32_e32 v127, v107
	v_sub_f32_e32 v107, v128, v205
	v_add_f32_e32 v106, v210, v106
	v_exp_f32_e32 v128, v107
	v_sub_f32_e32 v107, v129, v205
	v_add_f32_e32 v106, v211, v106
	v_exp_f32_e32 v129, v107
	v_sub_f32_e32 v107, v130, v205
	v_add_f32_e32 v106, v212, v106
	v_exp_f32_e32 v119, v107
	v_sub_f32_e32 v107, v131, v205
	v_add_f32_e32 v106, v127, v106
	v_exp_f32_e32 v120, v107
	v_sub_f32_e32 v107, v132, v205
	v_add_f32_e32 v106, v128, v106
	v_exp_f32_e32 v121, v107
	v_sub_f32_e32 v107, v133, v205
	v_add_f32_e32 v106, v129, v106
	v_exp_f32_e32 v122, v107
	v_add_f32_e32 v106, v119, v106
	v_add_f32_e32 v106, v120, v106
	v_add_f32_e32 v106, v121, v106
	v_sub_f32_e32 v204, v236, v205
	v_add_f32_e32 v118, v122, v106
	v_sub_f32_e32 v106, v134, v205
	v_exp_f32_e32 v204, v204
	v_exp_f32_e32 v123, v106
	v_sub_f32_e32 v106, v135, v205
	v_exp_f32_e32 v124, v106
	v_sub_f32_e32 v106, v136, v205
	v_exp_f32_e32 v125, v106
	v_sub_f32_e32 v106, v137, v205
	v_exp_f32_e32 v126, v106
	v_pk_mul_f32 v[110:111], v[22:23], v[204:205] op_sel_hi:[1,0]
	v_pk_mul_f32 v[22:23], v[18:19], v[204:205] op_sel_hi:[1,0]
	v_pk_mul_f32 v[18:19], v[30:31], v[204:205] op_sel_hi:[1,0]
	v_add_f32_e32 v30, v123, v118
	v_add_f32_e32 v30, v124, v30
	v_add_f32_e32 v30, v125, v30
	v_add_f32_e32 v118, v126, v30
	s_waitcnt vmcnt(15)
	v_cvt_pk_bf16_f32 v30, v98, v99
	v_cvt_pk_bf16_f32 v31, v100, v101
	ds_write_b64 v251, v[30:31]
	s_waitcnt vmcnt(14)
	v_cvt_pk_bf16_f32 v30, v94, v95
	v_cvt_pk_bf16_f32 v31, v96, v97
	ds_write_b64 v251, v[30:31] offset:576
	s_waitcnt vmcnt(13)
	v_cvt_pk_bf16_f32 v30, v90, v91
	v_cvt_pk_bf16_f32 v31, v92, v93
	ds_write_b64 v251, v[30:31] offset:1152
	s_waitcnt vmcnt(3)
	v_cvt_pk_bf16_f32 v30, v102, v103
	v_cvt_pk_bf16_f32 v31, v104, v105
	ds_write_b64 v251, v[30:31] offset:1728
	v_cvt_pk_bf16_f32 v30, v86, v87
	v_cvt_pk_bf16_f32 v31, v88, v89
	ds_write_b64 v251, v[30:31] offset:2304
	v_cvt_pk_bf16_f32 v30, v82, v83
	v_cvt_pk_bf16_f32 v31, v84, v85
	ds_write_b64 v251, v[30:31] offset:2880
	v_cvt_pk_bf16_f32 v30, v78, v79
	v_cvt_pk_bf16_f32 v31, v80, v81
	ds_write_b64 v251, v[30:31] offset:3456
	v_cvt_pk_bf16_f32 v30, v74, v75
	v_cvt_pk_bf16_f32 v31, v76, v77
	ds_write_b64 v251, v[30:31] offset:4032
	v_cvt_pk_bf16_f32 v30, v70, v71
	v_cvt_pk_bf16_f32 v31, v72, v73
	ds_write_b64 v251, v[30:31] offset:4608
	v_cvt_pk_bf16_f32 v30, v66, v67
	v_cvt_pk_bf16_f32 v31, v68, v69
	ds_write_b64 v251, v[30:31] offset:5184
	v_cvt_pk_bf16_f32 v30, v62, v63
	v_cvt_pk_bf16_f32 v31, v64, v65
	ds_write_b64 v251, v[30:31] offset:5760
	v_cvt_pk_bf16_f32 v30, v58, v59
	v_cvt_pk_bf16_f32 v31, v60, v61
	ds_write_b64 v251, v[30:31] offset:6336
	v_cvt_pk_bf16_f32 v30, v54, v55
	v_cvt_pk_bf16_f32 v31, v56, v57
	ds_write_b64 v251, v[30:31] offset:6912
	s_waitcnt vmcnt(1)
	v_cvt_pk_bf16_f32 v30, v50, v51
	v_cvt_pk_bf16_f32 v31, v52, v53
	ds_write_b64 v251, v[30:31] offset:7488
	v_cvt_pk_bf16_f32 v30, v46, v47
	v_cvt_pk_bf16_f32 v31, v48, v49
	ds_write_b64 v251, v[30:31] offset:8064
	s_waitcnt vmcnt(0)
	v_cvt_pk_bf16_f32 v30, v42, v43
	v_cvt_pk_bf16_f32 v31, v44, v45
	ds_write_b64 v251, v[30:31] offset:8640
	buffer_load_dwordx4 v[90:93], v248, s[16:19], s15 offen sc1 nt
	buffer_load_dwordx4 v[86:89], v248, s[16:19], s6 offen sc1 nt
	buffer_load_dwordx4 v[82:85], v248, s[16:19], s52 offen sc1 nt
	s_mov_b32 s6, 0x26000
	buffer_load_dwordx4 v[78:81], v248, s[16:19], s6 offen sc1 nt
	buffer_load_dwordx4 v[74:77], v248, s[16:19], s53 offen sc1 nt
	s_mov_b32 s6, 0x2a000
	buffer_load_dwordx4 v[70:73], v248, s[16:19], s6 offen sc1 nt
	buffer_load_dwordx4 v[66:69], v248, s[16:19], s54 offen sc1 nt
	s_mov_b32 s6, 0x2e000
	buffer_load_dwordx4 v[62:65], v248, s[16:19], s6 offen sc1 nt
	buffer_load_dwordx4 v[58:61], v248, s[16:19], s55 offen sc1 nt
	s_mov_b32 s6, 0x32000
	buffer_load_dwordx4 v[54:57], v248, s[16:19], s6 offen sc1 nt
	buffer_load_dwordx4 v[50:53], v248, s[16:19], s56 offen sc1 nt
	s_mov_b32 s6, 0x36000
	buffer_load_dwordx4 v[46:49], v248, s[16:19], s6 offen sc1 nt
	buffer_load_dwordx4 v[42:45], v248, s[16:19], s57 offen sc1 nt
	s_mov_b32 s6, 0x3a000
	v_pk_mul_f32 v[116:117], v[28:29], v[204:205] op_sel_hi:[1,0]
	v_pk_mul_f32 v[114:115], v[26:27], v[204:205] op_sel_hi:[1,0]
	v_pk_mul_f32 v[108:109], v[16:17], v[204:205] op_sel_hi:[1,0]
	v_pk_mul_f32 v[106:107], v[14:15], v[204:205] op_sel_hi:[1,0]
	v_pk_mul_f32 v[28:29], v[12:13], v[204:205] op_sel_hi:[1,0]
	v_pk_mul_f32 v[26:27], v[10:11], v[204:205] op_sel_hi:[1,0]
	v_pk_mul_f32 v[16:17], v[36:37], v[204:205] op_sel_hi:[1,0]
	v_pk_mul_f32 v[14:15], v[34:35], v[204:205] op_sel_hi:[1,0]
	v_pk_mul_f32 v[12:13], v[40:41], v[204:205] op_sel_hi:[1,0]
	v_pk_mul_f32 v[10:11], v[38:39], v[204:205] op_sel_hi:[1,0]
	buffer_load_dwordx4 v[38:41], v248, s[16:19], s6 offen sc1 nt
	buffer_load_dwordx4 v[34:37], v248, s[16:19], s62 offen sc1 nt
	s_mov_b32 s6, 0x3e000
	v_pk_mul_f32 v[112:113], v[24:25], v[204:205] op_sel_hi:[1,0]
	v_pk_mul_f32 v[24:25], v[20:21], v[204:205] op_sel_hi:[1,0]
	v_pk_mul_f32 v[20:21], v[32:33], v[204:205] op_sel_hi:[1,0]
	buffer_load_dwordx4 v[30:33], v248, s[16:19], s6 offen sc1 nt
	s_waitcnt lgkmcnt(0)
	v_cvt_pk_bf16_f32 v130, v221, v222
	v_cvt_pk_bf16_f32 v131, v223, v224
	v_cvt_pk_bf16_f32 v132, v225, v226
	v_cvt_pk_bf16_f32 v133, v227, v228
	ds_read_b64_tr_b16 v[96:97], v252 offset:4608
	ds_read_b64_tr_b16 v[94:95], v252
	ds_read_b64_tr_b16 v[98:99], v252 offset:32
	ds_read_b64_tr_b16 v[100:101], v252 offset:4640
	ds_read_b64_tr_b16 v[102:103], v252 offset:64
	ds_read_b64_tr_b16 v[104:105], v252 offset:4672
	s_waitcnt lgkmcnt(0)
	v_mfma_f32_16x16x32_bf16 v[102:105], v[102:105], v[130:133], v[106:109]
	s_nop 2
	ds_read_b64_tr_b16 v[106:107], v252 offset:96
	ds_read_b64_tr_b16 v[108:109], v252 offset:4704
	s_waitcnt lgkmcnt(0)
	v_mfma_f32_16x16x32_bf16 v[26:29], v[106:109], v[130:133], v[26:29]
	v_mfma_f32_16x16x32_bf16 v[94:97], v[94:97], v[130:133], v[114:117]
	v_mfma_f32_16x16x32_bf16 v[98:101], v[98:101], v[130:133], v[110:113]
	ds_read_b64_tr_b16 v[108:109], v252 offset:4736
	ds_read_b64_tr_b16 v[106:107], v252 offset:128
	s_nop 0
	ds_read_b64_tr_b16 v[110:111], v252 offset:160
	ds_read_b64_tr_b16 v[112:113], v252 offset:4768
	s_waitcnt lgkmcnt(2)
	v_mfma_f32_16x16x32_bf16 v[22:25], v[106:109], v[130:133], v[22:25]
	ds_read_b64_tr_b16 v[106:107], v252 offset:192
	ds_read_b64_tr_b16 v[108:109], v252 offset:4800
	s_waitcnt lgkmcnt(0)
	v_mfma_f32_16x16x32_bf16 v[14:17], v[106:109], v[130:133], v[14:17]
	ds_read_b64_tr_b16 v[106:107], v252 offset:224
	ds_read_b64_tr_b16 v[108:109], v252 offset:4832
	v_mfma_f32_16x16x32_bf16 v[18:21], v[110:113], v[130:133], v[18:21]
	s_waitcnt lgkmcnt(0)
	v_mfma_f32_16x16x32_bf16 v[10:13], v[106:109], v[130:133], v[10:13]
	s_waitcnt lgkmcnt(0)
	s_waitcnt vmcnt(15)
	v_cvt_pk_bf16_f32 v90, v90, v91
	v_cvt_pk_bf16_f32 v91, v92, v93
	ds_write_b64 v251, v[90:91]
	s_waitcnt vmcnt(14)
	v_cvt_pk_bf16_f32 v86, v86, v87
	v_cvt_pk_bf16_f32 v87, v88, v89
	ds_write_b64 v251, v[86:87] offset:576
	s_waitcnt vmcnt(13)
	v_cvt_pk_bf16_f32 v82, v82, v83
	v_cvt_pk_bf16_f32 v83, v84, v85
	ds_write_b64 v251, v[82:83] offset:1152
	s_waitcnt vmcnt(12)
	v_cvt_pk_bf16_f32 v78, v78, v79
	v_cvt_pk_bf16_f32 v79, v80, v81
	ds_write_b64 v251, v[78:79] offset:1728
	s_waitcnt vmcnt(11)
	v_cvt_pk_bf16_f32 v74, v74, v75
	v_cvt_pk_bf16_f32 v75, v76, v77
	ds_write_b64 v251, v[74:75] offset:2304
	s_waitcnt vmcnt(10)
	v_cvt_pk_bf16_f32 v70, v70, v71
	v_cvt_pk_bf16_f32 v71, v72, v73
	ds_write_b64 v251, v[70:71] offset:2880
	s_waitcnt vmcnt(9)
	v_cvt_pk_bf16_f32 v66, v66, v67
	v_cvt_pk_bf16_f32 v67, v68, v69
	ds_write_b64 v251, v[66:67] offset:3456
	s_waitcnt vmcnt(8)
	v_cvt_pk_bf16_f32 v62, v62, v63
	v_cvt_pk_bf16_f32 v63, v64, v65
	ds_write_b64 v251, v[62:63] offset:4032
	s_waitcnt vmcnt(7)
	v_cvt_pk_bf16_f32 v58, v58, v59
	v_cvt_pk_bf16_f32 v59, v60, v61
	ds_write_b64 v251, v[58:59] offset:4608
	s_waitcnt vmcnt(6)
	v_cvt_pk_bf16_f32 v54, v54, v55
	v_cvt_pk_bf16_f32 v55, v56, v57
	ds_write_b64 v251, v[54:55] offset:5184
	s_waitcnt vmcnt(5)
	v_cvt_pk_bf16_f32 v50, v50, v51
	v_cvt_pk_bf16_f32 v51, v52, v53
	ds_write_b64 v251, v[50:51] offset:5760
	s_waitcnt vmcnt(4)
	v_cvt_pk_bf16_f32 v46, v46, v47
	v_cvt_pk_bf16_f32 v47, v48, v49
	ds_write_b64 v251, v[46:47] offset:6336
	s_waitcnt vmcnt(3)
	v_cvt_pk_bf16_f32 v42, v42, v43
	v_cvt_pk_bf16_f32 v43, v44, v45
	ds_write_b64 v251, v[42:43] offset:6912
	s_waitcnt vmcnt(2)
	v_cvt_pk_bf16_f32 v38, v38, v39
	v_cvt_pk_bf16_f32 v39, v40, v41
	ds_write_b64 v251, v[38:39] offset:7488
	s_waitcnt vmcnt(1)
	v_cvt_pk_bf16_f32 v34, v34, v35
	v_cvt_pk_bf16_f32 v35, v36, v37
	ds_write_b64 v251, v[34:35] offset:8064
	s_waitcnt vmcnt(0)
	v_cvt_pk_bf16_f32 v30, v30, v31
	v_cvt_pk_bf16_f32 v31, v32, v33
	ds_write_b64 v251, v[30:31] offset:8640
	s_mov_b32 s6, 0x42000
	buffer_load_dwordx4 v[70:73], v248, s[16:19], s63 offen sc1 nt
	buffer_load_dwordx4 v[74:77], v248, s[16:19], s6 offen sc1 nt
	buffer_load_dwordx4 v[78:81], v248, s[16:19], s64 offen sc1 nt
	s_mov_b32 s6, 0x46000
	buffer_load_dwordx4 v[82:85], v248, s[16:19], s6 offen sc1 nt
	buffer_load_dwordx4 v[86:89], v248, s[16:19], s65 offen sc1 nt
	s_mov_b32 s6, 0x4a000
	buffer_load_dwordx4 v[90:93], v248, s[16:19], s6 offen sc1 nt
	buffer_load_dwordx4 v[106:109], v248, s[16:19], s66 offen sc1 nt
	s_mov_b32 s6, 0x4e000
	buffer_load_dwordx4 v[110:113], v248, s[16:19], s6 offen sc1 nt
	buffer_load_dwordx4 v[114:117], v248, s[16:19], s67 offen sc1 nt
	s_mov_b32 s6, 0x52000
	buffer_load_dwordx4 v[66:69], v248, s[16:19], s6 offen sc1 nt
	buffer_load_dwordx4 v[62:65], v248, s[16:19], s68 offen sc1 nt
	s_mov_b32 s6, 0x56000
	buffer_load_dwordx4 v[58:61], v248, s[16:19], s6 offen sc1 nt
	buffer_load_dwordx4 v[54:57], v248, s[16:19], s69 offen sc1 nt
	s_mov_b32 s6, 0x5a000
	buffer_load_dwordx4 v[50:53], v248, s[16:19], s6 offen sc1 nt
	buffer_load_dwordx4 v[46:49], v248, s[16:19], s84 offen sc1 nt
	s_mov_b32 s6, 0x5e000
	buffer_load_dwordx4 v[42:45], v248, s[16:19], s6 offen sc1 nt
	s_waitcnt lgkmcnt(0)
	v_cvt_pk_bf16_f32 v130, v213, v214
	v_cvt_pk_bf16_f32 v131, v215, v216
	v_cvt_pk_bf16_f32 v132, v217, v218
	v_cvt_pk_bf16_f32 v133, v219, v220
	ds_read_b64_tr_b16 v[32:33], v252 offset:4608
	ds_read_b64_tr_b16 v[30:31], v252
	ds_read_b64_tr_b16 v[34:35], v252 offset:32
	ds_read_b64_tr_b16 v[36:37], v252 offset:4640
	s_waitcnt lgkmcnt(2)
	v_mfma_f32_16x16x32_bf16 v[30:33], v[30:33], v[130:133], v[94:97]
	ds_read_b64_tr_b16 v[38:39], v252 offset:64
	ds_read_b64_tr_b16 v[40:41], v252 offset:4672
	s_nop 0
	ds_read_b64_tr_b16 v[94:95], v252 offset:96
	ds_read_b64_tr_b16 v[96:97], v252 offset:4704
	s_waitcnt lgkmcnt(4)
	v_mfma_f32_16x16x32_bf16 v[34:37], v[34:37], v[130:133], v[98:101]
	s_waitcnt lgkmcnt(2)
	v_mfma_f32_16x16x32_bf16 v[38:41], v[38:41], v[130:133], v[102:105]
	s_waitcnt lgkmcnt(0)
	v_mfma_f32_16x16x32_bf16 v[26:29], v[94:97], v[130:133], v[26:29]
	ds_read_b64_tr_b16 v[96:97], v252 offset:4736
	ds_read_b64_tr_b16 v[94:95], v252 offset:128
	ds_read_b64_tr_b16 v[98:99], v252 offset:160
	ds_read_b64_tr_b16 v[100:101], v252 offset:4768
	s_waitcnt lgkmcnt(2)
	v_mfma_f32_16x16x32_bf16 v[22:25], v[94:97], v[130:133], v[22:25]
	ds_read_b64_tr_b16 v[94:95], v252 offset:192
	ds_read_b64_tr_b16 v[96:97], v252 offset:4800
	s_waitcnt lgkmcnt(0)
	v_mfma_f32_16x16x32_bf16 v[14:17], v[94:97], v[130:133], v[14:17]
	ds_read_b64_tr_b16 v[94:95], v252 offset:224
	ds_read_b64_tr_b16 v[96:97], v252 offset:4832
	v_mfma_f32_16x16x32_bf16 v[18:21], v[98:101], v[130:133], v[18:21]
	s_waitcnt lgkmcnt(0)
	v_mfma_f32_16x16x32_bf16 v[10:13], v[94:97], v[130:133], v[10:13]
	s_waitcnt lgkmcnt(0)
	s_waitcnt vmcnt(15)
	v_cvt_pk_bf16_f32 v70, v70, v71
	v_cvt_pk_bf16_f32 v71, v72, v73
	ds_write_b64 v251, v[70:71]
	s_waitcnt vmcnt(14)
	v_cvt_pk_bf16_f32 v70, v74, v75
	v_cvt_pk_bf16_f32 v71, v76, v77
	ds_write_b64 v251, v[70:71] offset:576
	s_waitcnt vmcnt(13)
	v_cvt_pk_bf16_f32 v70, v78, v79
	v_cvt_pk_bf16_f32 v71, v80, v81
	ds_write_b64 v251, v[70:71] offset:1152
	s_waitcnt vmcnt(12)
	v_cvt_pk_bf16_f32 v70, v82, v83
	v_cvt_pk_bf16_f32 v71, v84, v85
	ds_write_b64 v251, v[70:71] offset:1728
	s_waitcnt vmcnt(11)
	v_cvt_pk_bf16_f32 v70, v86, v87
	v_cvt_pk_bf16_f32 v71, v88, v89
	ds_write_b64 v251, v[70:71] offset:2304
	s_waitcnt vmcnt(10)
	v_cvt_pk_bf16_f32 v70, v90, v91
	v_cvt_pk_bf16_f32 v71, v92, v93
	ds_write_b64 v251, v[70:71] offset:2880
	s_waitcnt vmcnt(9)
	v_cvt_pk_bf16_f32 v70, v106, v107
	v_cvt_pk_bf16_f32 v71, v108, v109
	ds_write_b64 v251, v[70:71] offset:3456
	s_waitcnt vmcnt(8)
	v_cvt_pk_bf16_f32 v70, v110, v111
	v_cvt_pk_bf16_f32 v71, v112, v113
	ds_write_b64 v251, v[70:71] offset:4032
	s_waitcnt vmcnt(7)
	v_cvt_pk_bf16_f32 v70, v114, v115
	v_cvt_pk_bf16_f32 v71, v116, v117
	ds_write_b64 v251, v[70:71] offset:4608
	s_waitcnt vmcnt(6)
	v_cvt_pk_bf16_f32 v66, v66, v67
	v_cvt_pk_bf16_f32 v67, v68, v69
	ds_write_b64 v251, v[66:67] offset:5184
	s_waitcnt vmcnt(5)
	v_cvt_pk_bf16_f32 v62, v62, v63
	v_cvt_pk_bf16_f32 v63, v64, v65
	ds_write_b64 v251, v[62:63] offset:5760
	s_waitcnt vmcnt(4)
	v_cvt_pk_bf16_f32 v58, v58, v59
	v_cvt_pk_bf16_f32 v59, v60, v61
	ds_write_b64 v251, v[58:59] offset:6336
	s_waitcnt vmcnt(3)
	v_cvt_pk_bf16_f32 v54, v54, v55
	v_cvt_pk_bf16_f32 v55, v56, v57
	ds_write_b64 v251, v[54:55] offset:6912
	s_waitcnt vmcnt(2)
	v_cvt_pk_bf16_f32 v50, v50, v51
	v_cvt_pk_bf16_f32 v51, v52, v53
	ds_write_b64 v251, v[50:51] offset:7488
	s_waitcnt vmcnt(1)
	v_cvt_pk_bf16_f32 v46, v46, v47
	v_cvt_pk_bf16_f32 v47, v48, v49
	ds_write_b64 v251, v[46:47] offset:8064
	s_waitcnt vmcnt(0)
	v_cvt_pk_bf16_f32 v42, v42, v43
	v_cvt_pk_bf16_f32 v43, v44, v45
	ds_write_b64 v251, v[42:43] offset:8640
	s_mov_b32 s6, 0x62000
	buffer_load_dwordx4 v[90:93], v248, s[16:19], s85 offen sc1 nt
	buffer_load_dwordx4 v[94:97], v248, s[16:19], s6 offen sc1 nt
	buffer_load_dwordx4 v[98:101], v248, s[16:19], s86 offen sc1 nt
	s_mov_b32 s6, 0x66000
	buffer_load_dwordx4 v[102:105], v248, s[16:19], s6 offen sc1 nt
	buffer_load_dwordx4 v[106:109], v248, s[16:19], s87 offen sc1 nt
	s_mov_b32 s6, 0x6a000
	buffer_load_dwordx4 v[110:113], v248, s[16:19], s6 offen sc1 nt
	buffer_load_dwordx4 v[114:117], v248, s[16:19], s92 offen sc1 nt
	s_mov_b32 s6, 0x6e000
	buffer_load_dwordx4 v[130:133], v248, s[16:19], s6 offen sc1 nt
	buffer_load_dwordx4 v[134:137], v248, s[16:19], s94 offen sc1 nt
	s_mov_b32 s6, 0x72000
	buffer_load_dwordx4 v[86:89], v248, s[16:19], s6 offen sc1 nt
	buffer_load_dwordx4 v[82:85], v248, s[16:19], s95 offen sc1 nt
	s_mov_b32 s6, 0x76000
	buffer_load_dwordx4 v[78:81], v248, s[16:19], s6 offen sc1 nt
	buffer_load_dwordx4 v[54:57], v248, s[16:19], s96 offen sc1 nt
	s_mov_b32 s6, 0x7a000
	buffer_load_dwordx4 v[50:53], v248, s[16:19], s6 offen sc1 nt
	buffer_load_dwordx4 v[46:49], v248, s[16:19], s97 offen sc1 nt
	s_mov_b32 s6, 0x7e000
	buffer_load_dwordx4 v[42:45], v248, s[16:19], s6 offen sc1 nt
	s_waitcnt lgkmcnt(0)
	v_cvt_pk_bf16_f32 v74, v208, v209
	v_cvt_pk_bf16_f32 v75, v210, v211
	v_cvt_pk_bf16_f32 v76, v212, v127
	v_cvt_pk_bf16_f32 v77, v128, v129
	ds_read_b64_tr_b16 v[60:61], v252 offset:4608
	ds_read_b64_tr_b16 v[58:59], v252
	ds_read_b64_tr_b16 v[62:63], v252 offset:32
	ds_read_b64_tr_b16 v[64:65], v252 offset:4640
	s_waitcnt lgkmcnt(2)
	v_mfma_f32_16x16x32_bf16 v[30:33], v[58:61], v[74:77], v[30:33]
	ds_read_b64_tr_b16 v[58:59], v252 offset:64
	ds_read_b64_tr_b16 v[60:61], v252 offset:4672
	s_waitcnt lgkmcnt(0)
	v_mfma_f32_16x16x32_bf16 v[38:41], v[58:61], v[74:77], v[38:41]
	ds_read_b64_tr_b16 v[58:59], v252 offset:96
	ds_read_b64_tr_b16 v[60:61], v252 offset:4704
	v_mfma_f32_16x16x32_bf16 v[34:37], v[62:65], v[74:77], v[34:37]
	s_waitcnt lgkmcnt(0)
	v_mfma_f32_16x16x32_bf16 v[58:61], v[58:61], v[74:77], v[26:29]
	s_nop 2
	ds_read_b64_tr_b16 v[28:29], v252 offset:4736
	ds_read_b64_tr_b16 v[26:27], v252 offset:128
	ds_read_b64_tr_b16 v[66:67], v252 offset:160
	ds_read_b64_tr_b16 v[68:69], v252 offset:4768
	s_waitcnt lgkmcnt(2)
	v_mfma_f32_16x16x32_bf16 v[62:65], v[26:29], v[74:77], v[22:25]
	s_waitcnt lgkmcnt(0)
	v_mfma_f32_16x16x32_bf16 v[66:69], v[66:69], v[74:77], v[18:21]
	s_nop 2
	ds_read_b64_tr_b16 v[18:19], v252 offset:192
	ds_read_b64_tr_b16 v[20:21], v252 offset:4800
	s_waitcnt lgkmcnt(0)
	v_mfma_f32_16x16x32_bf16 v[70:73], v[18:21], v[74:77], v[14:17]
	s_nop 2
	ds_read_b64_tr_b16 v[14:15], v252 offset:224
	ds_read_b64_tr_b16 v[16:17], v252 offset:4832
	s_waitcnt lgkmcnt(0)
	v_mfma_f32_16x16x32_bf16 v[74:77], v[14:17], v[74:77], v[10:13]
	s_waitcnt lgkmcnt(0)
	s_waitcnt vmcnt(15)
	v_cvt_pk_bf16_f32 v10, v90, v91
	v_cvt_pk_bf16_f32 v11, v92, v93
	ds_write_b64 v251, v[10:11]
	s_waitcnt vmcnt(14)
	v_cvt_pk_bf16_f32 v10, v94, v95
	v_cvt_pk_bf16_f32 v11, v96, v97
	ds_write_b64 v251, v[10:11] offset:576
	s_waitcnt vmcnt(13)
	v_cvt_pk_bf16_f32 v10, v98, v99
	v_cvt_pk_bf16_f32 v11, v100, v101
	ds_write_b64 v251, v[10:11] offset:1152
	s_waitcnt vmcnt(12)
	v_cvt_pk_bf16_f32 v10, v102, v103
	v_cvt_pk_bf16_f32 v11, v104, v105
	ds_write_b64 v251, v[10:11] offset:1728
	s_waitcnt vmcnt(11)
	v_cvt_pk_bf16_f32 v10, v106, v107
	v_cvt_pk_bf16_f32 v11, v108, v109
	ds_write_b64 v251, v[10:11] offset:2304
	s_waitcnt vmcnt(10)
	v_cvt_pk_bf16_f32 v10, v110, v111
	v_cvt_pk_bf16_f32 v11, v112, v113
	ds_write_b64 v251, v[10:11] offset:2880
	s_waitcnt vmcnt(9)
	v_cvt_pk_bf16_f32 v10, v114, v115
	v_cvt_pk_bf16_f32 v11, v116, v117
	ds_write_b64 v251, v[10:11] offset:3456
	s_waitcnt vmcnt(8)
	v_cvt_pk_bf16_f32 v10, v130, v131
	v_cvt_pk_bf16_f32 v11, v132, v133
	ds_write_b64 v251, v[10:11] offset:4032
	s_waitcnt vmcnt(7)
	v_cvt_pk_bf16_f32 v10, v134, v135
	v_cvt_pk_bf16_f32 v11, v136, v137
	ds_write_b64 v251, v[10:11] offset:4608
	s_waitcnt vmcnt(6)
	v_cvt_pk_bf16_f32 v10, v86, v87
	v_cvt_pk_bf16_f32 v11, v88, v89
	ds_write_b64 v251, v[10:11] offset:5184
	s_waitcnt vmcnt(5)
	v_cvt_pk_bf16_f32 v10, v82, v83
	v_cvt_pk_bf16_f32 v11, v84, v85
	ds_write_b64 v251, v[10:11] offset:5760
	s_waitcnt vmcnt(4)
	v_cvt_pk_bf16_f32 v10, v78, v79
	v_cvt_pk_bf16_f32 v11, v80, v81
	ds_write_b64 v251, v[10:11] offset:6336
	s_waitcnt vmcnt(3)
	v_cvt_pk_bf16_f32 v10, v54, v55
	v_cvt_pk_bf16_f32 v11, v56, v57
	ds_write_b64 v251, v[10:11] offset:6912
	s_waitcnt vmcnt(2)
	v_cvt_pk_bf16_f32 v10, v50, v51
	v_cvt_pk_bf16_f32 v11, v52, v53
	ds_write_b64 v251, v[10:11] offset:7488
	s_waitcnt vmcnt(1)
	v_cvt_pk_bf16_f32 v10, v46, v47
	v_cvt_pk_bf16_f32 v11, v48, v49
	ds_write_b64 v251, v[10:11] offset:8064
	s_waitcnt vmcnt(0)
	v_cvt_pk_bf16_f32 v10, v42, v43
	v_cvt_pk_bf16_f32 v11, v44, v45
	ds_write_b64 v251, v[10:11] offset:8640
	s_waitcnt lgkmcnt(0)
	v_cvt_pk_bf16_f32 v42, v119, v120
	v_cvt_pk_bf16_f32 v43, v121, v122
	v_cvt_pk_bf16_f32 v44, v123, v124
	v_cvt_pk_bf16_f32 v45, v125, v126
	ds_read_b64_tr_b16 v[10:11], v252
	ds_read_b64_tr_b16 v[12:13], v252 offset:4608
	ds_read_b64_tr_b16 v[16:17], v252 offset:4640
	ds_read_b64_tr_b16 v[14:15], v252 offset:32
	ds_read_b64_tr_b16 v[18:19], v252 offset:64
	ds_read_b64_tr_b16 v[46:47], v252 offset:96
	ds_read_b64_tr_b16 v[20:21], v252 offset:4672
	ds_read_b64_tr_b16 v[48:49], v252 offset:4704
	s_waitcnt lgkmcnt(6)
	v_mfma_f32_16x16x32_bf16 v[26:29], v[10:13], v[42:45], v[30:33]
	s_waitcnt lgkmcnt(4)
	v_mfma_f32_16x16x32_bf16 v[22:25], v[14:17], v[42:45], v[34:37]
	s_waitcnt lgkmcnt(1)
	v_mfma_f32_16x16x32_bf16 v[14:17], v[18:21], v[42:45], v[38:41]
	s_waitcnt lgkmcnt(0)
	v_mfma_f32_16x16x32_bf16 v[10:13], v[46:49], v[42:45], v[58:61]
	ds_read_b64_tr_b16 v[20:21], v252 offset:4736
	ds_read_b64_tr_b16 v[18:19], v252 offset:128
	ds_read_b64_tr_b16 v[30:31], v252 offset:160
	ds_read_b64_tr_b16 v[32:33], v252 offset:4768
	ds_read_b64_tr_b16 v[34:35], v252 offset:192
	ds_read_b64_tr_b16 v[36:37], v252 offset:4800
	ds_read_b64_tr_b16 v[38:39], v252 offset:224
	ds_read_b64_tr_b16 v[40:41], v252 offset:4832
	s_waitcnt lgkmcnt(6)
	v_mfma_f32_16x16x32_bf16 v[18:21], v[18:21], v[42:45], v[62:65]
	s_waitcnt lgkmcnt(2)
	v_mfma_f32_16x16x32_bf16 v[34:37], v[34:37], v[42:45], v[70:73]
	v_mfma_f32_16x16x32_bf16 v[30:33], v[30:33], v[42:45], v[66:69]
	s_waitcnt lgkmcnt(0)
	v_mfma_f32_16x16x32_bf16 v[38:41], v[38:41], v[42:45], v[74:77]
	s_waitcnt lgkmcnt(0)
	s_add_i32 s5, s5, 1
	s_add_u32 s30, s30, 4
	s_addc_u32 s31, s31, 0
	s_cmp_eq_u32 s5, 8
	v_fmac_f32_e32 v118, v253, v204
	s_cbranch_scc1 .LBB0_727
	v_mov_b32_e32 v253, v118
	v_mov_b32_e32 v236, v205
	s_branch .LBB0_721
